# w_out phase epilogue (x += gt*acc): the 8 residual-row and 8 gate-vector loads of each 32-row block are issued together and consumed under counted vmcnt instead of load-wait-store per 16 bytes
# speedup vs baseline: 1.0078x; 1.0078x over previous
; template <int MB>
; DI void out_tile(const Params& P, int layer, int row0, int nt, char* smem) {
;     ...
; #pragma unroll
;     for (int nb = 0; nb < 2; ++nb)
; #pragma unroll
;       for (int g = 0; g < 4; ++g) {
;         const int col = nt * 256 + wc * 64 + nb * 32 + 8 * g + 4 * hh;
;         const float4 xo = *(const float4*)(src + col);
;         const float4 gv = *(const float4*)(gt + col);
;         float4 r;
;         r.x = xo.x + gv.x * acc[mb][nb][4 * g]; r.y = xo.y + gv.y * acc[mb][nb][4 * g + 1];
;         r.z = xo.z + gv.z * acc[mb][nb][4 * g + 2]; r.w = xo.w + gv.w * acc[mb][nb][4 * g + 3];
;         *(float4*)(dst + col) = r;
;       }
.LBB0_719:
	s_or_b64 exec, exec, s[2:3]
	v_lshl_add_u64 v[40:41], v[42:43], 2, s[40:41]
	s_mov_b64 s[2:3], 0x1002000
	v_lshl_add_u64 v[42:43], v[40:41], 0, s[2:3]
	v_lshl_add_u64 v[40:41], v[38:39], 0, v[128:129]
	v_lshl_add_u64 v[56:57], v[42:43], 0, v[128:129]
	v_lshl_add_u64 v[38:39], v[44:45], 0, v[128:129]
	global_load_dwordx4 v[162:165], v[56:57], off
	global_load_dwordx4 v[166:169], v[56:57], off offset:32
	global_load_dwordx4 v[170:173], v[56:57], off offset:64
	global_load_dwordx4 v[174:177], v[56:57], off offset:96
	global_load_dwordx4 v[178:181], v[56:57], off offset:128
	global_load_dwordx4 v[182:185], v[56:57], off offset:160
	global_load_dwordx4 v[186:189], v[56:57], off offset:192
	global_load_dwordx4 v[190:193], v[56:57], off offset:224
	global_load_dwordx4 v[130:133], v[40:41], off
	global_load_dwordx4 v[134:137], v[40:41], off offset:32
	global_load_dwordx4 v[138:141], v[40:41], off offset:64
	global_load_dwordx4 v[142:145], v[40:41], off offset:96
	global_load_dwordx4 v[146:149], v[40:41], off offset:128
	global_load_dwordx4 v[150:153], v[40:41], off offset:160
	global_load_dwordx4 v[154:157], v[40:41], off offset:192
	global_load_dwordx4 v[158:161], v[40:41], off offset:224
	s_waitcnt vmcnt(7)
	v_pk_fma_f32 v[16:17], v[16:17], v[162:163], v[130:131]
	v_pk_fma_f32 v[18:19], v[18:19], v[164:165], v[132:133]
	global_store_dwordx4 v[38:39], v[16:19], off
	s_waitcnt vmcnt(7)
	v_pk_fma_f32 v[20:21], v[20:21], v[166:167], v[134:135]
	v_pk_fma_f32 v[22:23], v[22:23], v[168:169], v[136:137]
	global_store_dwordx4 v[38:39], v[20:23], off offset:32
	s_waitcnt vmcnt(7)
	v_pk_fma_f32 v[24:25], v[24:25], v[170:171], v[138:139]
	v_pk_fma_f32 v[26:27], v[26:27], v[172:173], v[140:141]
	global_store_dwordx4 v[38:39], v[24:27], off offset:64
	s_waitcnt vmcnt(7)
	v_pk_fma_f32 v[28:29], v[28:29], v[174:175], v[142:143]
	v_pk_fma_f32 v[30:31], v[30:31], v[176:177], v[144:145]
	global_store_dwordx4 v[38:39], v[28:31], off offset:96
	s_waitcnt vmcnt(7)
	v_pk_fma_f32 v[0:1], v[0:1], v[178:179], v[146:147]
	v_pk_fma_f32 v[2:3], v[2:3], v[180:181], v[148:149]
	global_store_dwordx4 v[38:39], v[0:3], off offset:128
	s_waitcnt vmcnt(7)
	v_pk_fma_f32 v[4:5], v[4:5], v[182:183], v[150:151]
	v_pk_fma_f32 v[6:7], v[6:7], v[184:185], v[152:153]
	global_store_dwordx4 v[38:39], v[4:7], off offset:160
	s_waitcnt vmcnt(7)
	v_pk_fma_f32 v[8:9], v[8:9], v[186:187], v[154:155]
	v_pk_fma_f32 v[10:11], v[10:11], v[188:189], v[156:157]
	global_store_dwordx4 v[38:39], v[8:11], off offset:192
	s_waitcnt vmcnt(7)
	v_pk_fma_f32 v[12:13], v[12:13], v[190:191], v[158:159]
	v_pk_fma_f32 v[14:15], v[14:15], v[192:193], v[160:161]
	global_store_dwordx4 v[38:39], v[12:15], off offset:224

; template <int MB>
; DI void out_tile(const Params& P, int layer, int row0, int nt, char* smem) {
;     ...
; #pragma unroll
;   for (int mb = 0; mb < MB; ++mb) {
;     const int row = row0 + wr * 32 * MB + mb * 32 + r32;
;     const float* src; float* dst; int b;
;     if (row < T_LAT) { b = row >> 11; src = (layer == 0 ? P.x : P.out) + (size_t)row * D; dst = P.out + (size_t)row * D; }
;     else { const int rc = row - T_LAT; b = 16; src = (layer == 0 ? P.ctx : ctxw) + (size_t)rc * D; dst = ctxw + (size_t)rc * D; }
;     const float* gt = mods + b * 3072 + 2048;
; #pragma unroll
;     for (int nb = 0; nb < 2; ++nb)
; #pragma unroll
;       for (int g = 0; g < 4; ++g) {
;         const int col = nt * 256 + wc * 64 + nb * 32 + 8 * g + 4 * hh;
;         const float4 xo = *(const float4*)(src + col);
;         const float4 gv = *(const float4*)(gt + col);
;         float4 r;
;         r.x = xo.x + gv.x * acc[mb][nb][4 * g]; r.y = xo.y + gv.y * acc[mb][nb][4 * g + 1];
;         r.z = xo.z + gv.z * acc[mb][nb][4 * g + 2]; r.w = xo.w + gv.w * acc[mb][nb][4 * g + 3];
;         *(float4*)(dst + col) = r;
;       }
.LBB0_728:
	s_or_b64 exec, exec, s[2:3]
	v_and_b32_e32 v65, 0xc0, v70
	v_lshrrev_b32_e32 v70, 3, v70
	s_lshl_b32 s2, s75, 8
	v_and_b32_e32 v70, 4, v70
	v_or3_b32 v65, v65, s2, v70
	v_lshl_add_u64 v[68:69], v[68:69], 2, s[40:41]
	s_mov_b64 s[2:3], 0x1002000
	v_lshl_add_u64 v[70:71], v[68:69], 0, s[2:3]
	v_lshlrev_b32_e32 v128, 2, v65
	v_lshl_add_u64 v[68:69], v[66:67], 0, v[128:129]
	v_lshl_add_u64 v[76:77], v[70:71], 0, v[128:129]
	v_lshl_add_u64 v[66:67], v[72:73], 0, v[128:129]
	s_movk_i32 s2, 0x7fff
	global_load_dwordx4 v[162:165], v[76:77], off
	global_load_dwordx4 v[166:169], v[76:77], off offset:32
	global_load_dwordx4 v[170:173], v[76:77], off offset:64
	global_load_dwordx4 v[174:177], v[76:77], off offset:96
	global_load_dwordx4 v[178:181], v[76:77], off offset:128
	global_load_dwordx4 v[182:185], v[76:77], off offset:160
	global_load_dwordx4 v[186:189], v[76:77], off offset:192
	global_load_dwordx4 v[190:193], v[76:77], off offset:224
	global_load_dwordx4 v[130:133], v[68:69], off
	global_load_dwordx4 v[134:137], v[68:69], off offset:32
	global_load_dwordx4 v[138:141], v[68:69], off offset:64
	global_load_dwordx4 v[142:145], v[68:69], off offset:96
	global_load_dwordx4 v[146:149], v[68:69], off offset:128
	global_load_dwordx4 v[150:153], v[68:69], off offset:160
	global_load_dwordx4 v[154:157], v[68:69], off offset:192
	global_load_dwordx4 v[158:161], v[68:69], off offset:224
	s_waitcnt vmcnt(7)
	v_pk_fma_f32 v[48:49], v[48:49], v[162:163], v[130:131]
	v_pk_fma_f32 v[50:51], v[50:51], v[164:165], v[132:133]
	global_store_dwordx4 v[66:67], v[48:51], off
	s_waitcnt vmcnt(7)
	v_pk_fma_f32 v[52:53], v[52:53], v[166:167], v[134:135]
	v_pk_fma_f32 v[54:55], v[54:55], v[168:169], v[136:137]
	global_store_dwordx4 v[66:67], v[52:55], off offset:32
	s_waitcnt vmcnt(7)
	v_pk_fma_f32 v[56:57], v[56:57], v[170:171], v[138:139]
	v_pk_fma_f32 v[58:59], v[58:59], v[172:173], v[140:141]
	global_store_dwordx4 v[66:67], v[56:59], off offset:64
	s_waitcnt vmcnt(7)
	v_pk_fma_f32 v[60:61], v[60:61], v[174:175], v[142:143]
	v_pk_fma_f32 v[62:63], v[62:63], v[176:177], v[144:145]
	global_store_dwordx4 v[66:67], v[60:63], off offset:96
	s_waitcnt vmcnt(7)
	v_pk_fma_f32 v[32:33], v[32:33], v[178:179], v[146:147]
	v_pk_fma_f32 v[34:35], v[34:35], v[180:181], v[148:149]
	global_store_dwordx4 v[66:67], v[32:35], off offset:128
	s_waitcnt vmcnt(7)
	v_pk_fma_f32 v[36:37], v[36:37], v[182:183], v[150:151]
	v_pk_fma_f32 v[38:39], v[38:39], v[184:185], v[152:153]
	global_store_dwordx4 v[66:67], v[36:39], off offset:160
	s_waitcnt vmcnt(7)
	v_pk_fma_f32 v[40:41], v[40:41], v[186:187], v[154:155]
	v_pk_fma_f32 v[42:43], v[42:43], v[188:189], v[156:157]
	global_store_dwordx4 v[66:67], v[40:43], off offset:192
	s_waitcnt vmcnt(7)
	v_pk_fma_f32 v[44:45], v[44:45], v[190:191], v[158:159]
	v_pk_fma_f32 v[46:47], v[46:47], v[192:193], v[160:161]
	global_store_dwordx4 v[66:67], v[44:47], off offset:224
	s_nop 1
	v_or_b32_e32 v48, 8, v65
	v_lshlrev_b32_e32 v48, 2, v48
	v_or_b32_e32 v50, 16, v65
	v_lshlrev_b32_e32 v50, 2, v50
	v_or_b32_e32 v52, 24, v65
	v_lshlrev_b32_e32 v52, 2, v52
	v_or_b32_e32 v54, 32, v65
	v_lshlrev_b32_e32 v54, 2, v54
	v_or_b32_e32 v32, 40, v65
	v_lshlrev_b32_e32 v32, 2, v32
	v_or_b32_e32 v34, 48, v65
	v_lshlrev_b32_e32 v34, 2, v34
	v_or_b32_e32 v36, 56, v65
	v_lshlrev_b32_e32 v36, 2, v36
	s_nop 1
	v_or_b32_e32 v40, 32, v64
	v_cmp_lt_i32_e32 vcc, s2, v40
	s_and_saveexec_b64 s[2:3], vcc
	s_xor_b64 s[2:3], exec, s[2:3]
	s_cbranch_execz .LBB0_730
	v_readlane_b32 s48, v253, 1
	v_add_u32_e32 v38, 0xffff8020, v64
	v_mov_b32_e32 v39, v129
	v_readlane_b32 s49, v253, 2
	v_lshlrev_b64 v[40:41], 12, v[38:39]
	v_readlane_b32 s62, v253, 15
	v_readlane_b32 s63, v253, 16
	v_readlane_b32 s48, v255, 30
	v_lshl_add_u64 v[38:39], s[42:43], 0, v[40:41]
	v_readlane_b32 s49, v255, 31
	v_lshl_add_u64 v[44:45], s[62:63], 0, v[40:41]
	v_readlane_b32 s50, v253, 3
	v_readlane_b32 s51, v253, 4
	v_readlane_b32 s52, v253, 5
	v_readlane_b32 s53, v253, 6
	v_readlane_b32 s54, v253, 7
	v_readlane_b32 s55, v253, 8
	v_readlane_b32 s56, v253, 9
	v_readlane_b32 s57, v253, 10
	v_readlane_b32 s58, v253, 11
	v_readlane_b32 s59, v253, 12
	v_readlane_b32 s60, v253, 13
	v_readlane_b32 s61, v253, 14
